# P5/P6 K-loop MFMA bursts: priority flip pair every 8 MFMAs (was one per 16)
# speedup vs baseline: 1.0004x; 1.0004x over previous
; #define PG8_LDA(dst, b, h) do { if constexpr (FP8) { _Pragma("unroll") for (int m = 0; m < 4; ++m) dst##8[m] = PG8_LD8(PG8_SA(b, h), aoff, aoff1, m); } \
;         else { _Pragma("unroll") for (int m = 0; m < 4; ++m) _Pragma("unroll") for (int k = 0; k < 2; ++k) dst[m][k] = *(const LAS bf16x8*)(lds + PG8_SA(b, h) + (k ? aoff1 : aoff) + m * 2048); } } while (0)
; #define PG8_LDB(dst, b, h) do { if constexpr (FP8) { dst##8[0] = PG8_LD8(PG8_SB(b, h), boff, boff1, 0); dst##8[1] = PG8_LD8(PG8_SB(b, h), boff, boff1, 1); } \
;         else { _Pragma("unroll") for (int n = 0; n < 2; ++n) _Pragma("unroll") for (int k = 0; k < 2; ++k) dst[n][k] = *(const LAS bf16x8*)(lds + PG8_SB(b, h) + (k ? boff1 : boff) + n * 2048); } } while (0)
; #define PG8_WAIT_V(n) asm volatile("s_waitcnt vmcnt(" #n ")" ::: "memory")
; #define PG8_WAIT_L(n) asm volatile("s_waitcnt lgkmcnt(" #n ")" ::: "memory")
; #define PG8_BAR __builtin_amdgcn_s_barrier()
; #define PG8_SCHED __builtin_amdgcn_sched_barrier(0)
; #define PG8_S1 PG8_STAGE(PG8_SA(1, 1), a1 + hstepA, voffA)
; #define PG8_S2 do { PG8_STAGE(PG8_SB(0, 0), b2, voffB); PG8_STAGE(PG8_SB(0, 1), b2 + hstepB, voffB); PG8_STAGE(PG8_SA(0, 0), a2, voffA); } while (0)
; template <class Epi, class SchedT, bool ALIGN_EPI, bool SP2, bool FP8 = false>
; __device__ __forceinline__ void gemm_phase(LAS unsigned char* lds, const Gemm g, const SchedT& S, const Epi& E, const int wid) {
;     ...
;             const bool last = (t == nt - 2);
;             const char* a1 = cA + (size_t)(t + 1) * kstep;
;             const char* a2 = last ? nA : cA + (size_t)(t + 2) * kstep; const char* b2 = last ? nB : cB + (size_t)(t + 2) * kstep;
;             const char* a3 = a2 + kstep; const char* b3 = b2 + kstep;
;             if constexpr (SP2) {
;     ...
;             PG8_LDB(B0, 0, 0); PG8_LDB(B1, 0, 1); PG8_SCHED; PG8_LDA(At, 0, 0); PG8_S1;
;             PG8_WAIT_V(8); PG8_WAIT_L(0); PG8_BAR; PG8_MMAP(0, 0, 0); PG8_BAR; PG8_SCHED;
;             PG8_LDA(At, 0, 1); PG8_S2;
;             PG8_WAIT_V(8); PG8_WAIT_L(0); PG8_BAR; PG8_MMAP(1, 0, 1); PG8_BAR; PG8_SCHED;
.LBB0_899:
	ds_read_b128 v[128:131], v173
	ds_read_b128 v[132:135], v173 offset:1024
	ds_read_b128 v[136:139], v174
	ds_read_b128 v[140:143], v174 offset:1024
	ds_read_b128 v[150:153], v175
	ds_read_b128 v[154:157], v175 offset:1024
	ds_read_b128 v[158:161], v176
	ds_read_b128 v[162:165], v176 offset:1024
	s_add_i32 s35, s34, 2
	s_add_u32 s16, s48, 0xfffc0080
	s_addc_u32 s17, s49, -1
	s_cmp_eq_u32 s27, s34
	s_cselect_b32 s51, s15, s17
	s_cselect_b32 s50, s21, s16
	s_cselect_b32 s53, s24, s31
	s_cselect_b32 s52, s25, s30
	v_mov_b32_e32 v144, v168
	ds_read_b128 v[182:185], v177
	ds_read_b128 v[186:189], v177 offset:1024
	ds_read_b128 v[190:193], v177 offset:2048
	ds_read_b128 v[194:197], v177 offset:3072
	ds_read_b128 v[198:201], v177 offset:4096
	ds_read_b128 v[202:205], v177 offset:5120
	ds_read_b128 v[206:209], v177 offset:6144
	ds_read_b128 v[210:213], v177 offset:7168
	s_add_i32 m0, s87, 0xc000
	s_nop 0
	global_load_lds_dwordx4 v144, s[48:49]
	v_mov_b32_e32 v144, v170
	s_add_i32 m0, s87, 0xe000
	s_nop 0
	global_load_lds_dwordx4 v144, s[48:49]
	s_waitcnt vmcnt(8)
	s_waitcnt lgkmcnt(0)
	s_barrier
	s_setprio 1
	s_waitcnt lgkmcnt(0)
	v_mfma_f32_16x16x32_bf16 v[124:127], v[128:131], v[182:185], v[124:127]
	v_mfma_f32_16x16x32_bf16 v[120:123], v[136:139], v[182:185], v[120:123]
	v_mfma_f32_16x16x32_bf16 v[108:111], v[128:131], v[190:193], v[108:111]
	v_mfma_f32_16x16x32_bf16 v[104:107], v[136:139], v[190:193], v[104:107]
	v_mfma_f32_16x16x32_bf16 v[92:95], v[128:131], v[198:201], v[92:95]
	v_mfma_f32_16x16x32_bf16 v[88:91], v[136:139], v[198:201], v[88:91]
	v_mfma_f32_16x16x32_bf16 v[76:79], v[128:131], v[206:209], v[76:79]
	v_mfma_f32_16x16x32_bf16 v[72:75], v[136:139], v[206:209], v[72:75]
	s_setprio 0
	s_setprio 1
	v_mfma_f32_16x16x32_bf16 v[124:127], v[132:135], v[186:189], v[124:127]
	v_mfma_f32_16x16x32_bf16 v[120:123], v[140:143], v[186:189], v[120:123]
	v_mfma_f32_16x16x32_bf16 v[108:111], v[132:135], v[194:197], v[108:111]
	v_mfma_f32_16x16x32_bf16 v[104:107], v[140:143], v[194:197], v[104:107]
	v_mfma_f32_16x16x32_bf16 v[92:95], v[132:135], v[202:205], v[92:95]
	v_mfma_f32_16x16x32_bf16 v[88:91], v[140:143], v[202:205], v[88:91]
	v_mfma_f32_16x16x32_bf16 v[76:79], v[132:135], v[210:213], v[76:79]
	v_mfma_f32_16x16x32_bf16 v[72:75], v[140:143], v[210:213], v[72:75]
	s_setprio 0
	s_setprio 1
	v_mfma_f32_16x16x32_bf16 v[116:119], v[150:153], v[182:185], v[116:119]
	v_mfma_f32_16x16x32_bf16 v[112:115], v[158:161], v[182:185], v[112:115]
	v_mfma_f32_16x16x32_bf16 v[100:103], v[150:153], v[190:193], v[100:103]
	v_mfma_f32_16x16x32_bf16 v[96:99], v[158:161], v[190:193], v[96:99]
	v_mfma_f32_16x16x32_bf16 v[84:87], v[150:153], v[198:201], v[84:87]
	v_mfma_f32_16x16x32_bf16 v[80:83], v[158:161], v[198:201], v[80:83]
	v_mfma_f32_16x16x32_bf16 v[68:71], v[150:153], v[206:209], v[68:71]
	v_mfma_f32_16x16x32_bf16 v[64:67], v[158:161], v[206:209], v[64:67]
	s_setprio 0
	s_setprio 1
	v_mfma_f32_16x16x32_bf16 v[116:119], v[154:157], v[186:189], v[116:119]
	v_mfma_f32_16x16x32_bf16 v[112:115], v[162:165], v[186:189], v[112:115]
	v_mfma_f32_16x16x32_bf16 v[100:103], v[154:157], v[194:197], v[100:103]
	v_mfma_f32_16x16x32_bf16 v[96:99], v[162:165], v[194:197], v[96:99]
	v_mfma_f32_16x16x32_bf16 v[84:87], v[154:157], v[202:205], v[84:87]
	v_mfma_f32_16x16x32_bf16 v[80:83], v[162:165], v[202:205], v[80:83]
	v_mfma_f32_16x16x32_bf16 v[68:71], v[154:157], v[210:213], v[68:71]
	v_mfma_f32_16x16x32_bf16 v[64:67], v[162:165], v[210:213], v[64:67]
	s_setprio 0
	s_barrier
	v_mov_b32_e32 v144, v169
	s_add_i32 s16, s94, s86
	ds_read_b128 v[182:185], v177 offset:16384
	ds_read_b128 v[186:189], v177 offset:17408
	ds_read_b128 v[190:193], v177 offset:18432
	ds_read_b128 v[194:197], v177 offset:19456
	ds_read_b128 v[198:201], v177 offset:20480
	ds_read_b128 v[202:205], v177 offset:21504
	ds_read_b128 v[206:209], v177 offset:22528
	ds_read_b128 v[210:213], v177 offset:23552
	s_mov_b32 m0, s16
	s_nop 0
	global_load_lds_dwordx4 v144, s[52:53]
	v_mov_b32_e32 v144, v171
	s_add_i32 m0, s16, 0x2000
	s_add_u32 s60, s52, 0x40000
	global_load_lds_dwordx4 v144, s[52:53]
	s_addc_u32 s61, s53, 0
	v_mov_b32_e32 v144, v169
	s_add_i32 s16, s95, s86
	s_mov_b32 m0, s16
	s_nop 0
	global_load_lds_dwordx4 v144, s[60:61]
	v_mov_b32_e32 v144, v171
	s_add_i32 m0, s16, 0x2000
	s_nop 0
	global_load_lds_dwordx4 v144, s[60:61]
	v_mov_b32_e32 v144, v168
	s_mov_b32 m0, s87
	s_nop 0
	global_load_lds_dwordx4 v144, s[50:51]
	v_mov_b32_e32 v144, v170
	s_mov_b32 m0, s88
	s_nop 0
	global_load_lds_dwordx4 v144, s[50:51]
	s_waitcnt vmcnt(8)
	s_waitcnt lgkmcnt(0)
	s_barrier
; #define PG8_LDA(dst, b, h) do { if constexpr (FP8) { _Pragma("unroll") for (int m = 0; m < 4; ++m) dst##8[m] = PG8_LD8(PG8_SA(b, h), aoff, aoff1, m); } \
;         else { _Pragma("unroll") for (int m = 0; m < 4; ++m) _Pragma("unroll") for (int k = 0; k < 2; ++k) dst[m][k] = *(const LAS bf16x8*)(lds + PG8_SA(b, h) + (k ? aoff1 : aoff) + m * 2048); } } while (0)
; #define PG8_LDB(dst, b, h) do { if constexpr (FP8) { dst##8[0] = PG8_LD8(PG8_SB(b, h), boff, boff1, 0); dst##8[1] = PG8_LD8(PG8_SB(b, h), boff, boff1, 1); } \
;         else { _Pragma("unroll") for (int n = 0; n < 2; ++n) _Pragma("unroll") for (int k = 0; k < 2; ++k) dst[n][k] = *(const LAS bf16x8*)(lds + PG8_SB(b, h) + (k ? boff1 : boff) + n * 2048); } } while (0)
; #define PG8_WAIT_V(n) asm volatile("s_waitcnt vmcnt(" #n ")" ::: "memory")
; #define PG8_WAIT_L(n) asm volatile("s_waitcnt lgkmcnt(" #n ")" ::: "memory")
; #define PG8_BAR __builtin_amdgcn_s_barrier()
; #define PG8_SCHED __builtin_amdgcn_sched_barrier(0)
; #define PG8_S3 PG8_STAGE(PG8_SA(0, 1), a2 + hstepA, voffA)
; template <class Epi, class SchedT, bool ALIGN_EPI, bool SP2, bool FP8 = false>
; __device__ __forceinline__ void gemm_phase(LAS unsigned char* lds, const Gemm g, const SchedT& S, const Epi& E, const int wid) {
;     ...
;             PG8_WAIT_V(8); PG8_WAIT_L(0); PG8_BAR; PG8_MMAP(1, 0, 1); PG8_BAR; PG8_SCHED;
;             PG8_LDB(B0, 1, 0); PG8_LDB(B1, 1, 1); PG8_SCHED; PG8_LDA(At, 1, 0); PG8_S3;
;             PG8_WAIT_V(8); PG8_WAIT_L(0); PG8_BAR; PG8_MMAP(0, 1, 0); PG8_BAR; PG8_SCHED;
	s_setprio 1
	s_waitcnt lgkmcnt(0)
	v_mfma_f32_16x16x32_bf16 v[60:63], v[128:131], v[182:185], v[60:63]
	v_mfma_f32_16x16x32_bf16 v[56:59], v[136:139], v[182:185], v[56:59]
	v_mfma_f32_16x16x32_bf16 v[44:47], v[128:131], v[190:193], v[44:47]
	v_mfma_f32_16x16x32_bf16 v[40:43], v[136:139], v[190:193], v[40:43]
	v_mfma_f32_16x16x32_bf16 v[28:31], v[128:131], v[198:201], v[28:31]
	v_mfma_f32_16x16x32_bf16 v[24:27], v[136:139], v[198:201], v[24:27]
	v_mfma_f32_16x16x32_bf16 v[12:15], v[128:131], v[206:209], v[12:15]
	v_mfma_f32_16x16x32_bf16 v[8:11], v[136:139], v[206:209], v[8:11]
	s_setprio 0
	s_setprio 1
	v_mfma_f32_16x16x32_bf16 v[60:63], v[132:135], v[186:189], v[60:63]
	v_mfma_f32_16x16x32_bf16 v[56:59], v[140:143], v[186:189], v[56:59]
	v_mfma_f32_16x16x32_bf16 v[44:47], v[132:135], v[194:197], v[44:47]
	v_mfma_f32_16x16x32_bf16 v[40:43], v[140:143], v[194:197], v[40:43]
	v_mfma_f32_16x16x32_bf16 v[28:31], v[132:135], v[202:205], v[28:31]
	v_mfma_f32_16x16x32_bf16 v[24:27], v[140:143], v[202:205], v[24:27]
	v_mfma_f32_16x16x32_bf16 v[12:15], v[132:135], v[210:213], v[12:15]
	v_mfma_f32_16x16x32_bf16 v[8:11], v[140:143], v[210:213], v[8:11]
	s_setprio 0
	s_setprio 1
	v_mfma_f32_16x16x32_bf16 v[52:55], v[150:153], v[182:185], v[52:55]
	v_mfma_f32_16x16x32_bf16 v[48:51], v[158:161], v[182:185], v[48:51]
	v_mfma_f32_16x16x32_bf16 v[36:39], v[150:153], v[190:193], v[36:39]
	v_mfma_f32_16x16x32_bf16 v[32:35], v[158:161], v[190:193], v[32:35]
	v_mfma_f32_16x16x32_bf16 v[20:23], v[150:153], v[198:201], v[20:23]
	v_mfma_f32_16x16x32_bf16 v[16:19], v[158:161], v[198:201], v[16:19]
	v_mfma_f32_16x16x32_bf16 v[4:7], v[150:153], v[206:209], v[4:7]
	v_mfma_f32_16x16x32_bf16 v[0:3], v[158:161], v[206:209], v[0:3]
	s_setprio 0
	s_setprio 1
	v_mfma_f32_16x16x32_bf16 v[52:55], v[154:157], v[186:189], v[52:55]
	v_mfma_f32_16x16x32_bf16 v[48:51], v[162:165], v[186:189], v[48:51]
	v_mfma_f32_16x16x32_bf16 v[36:39], v[154:157], v[194:197], v[36:39]
	v_mfma_f32_16x16x32_bf16 v[32:35], v[162:165], v[194:197], v[32:35]
	v_mfma_f32_16x16x32_bf16 v[20:23], v[154:157], v[202:205], v[20:23]
	v_mfma_f32_16x16x32_bf16 v[16:19], v[162:165], v[202:205], v[16:19]
	v_mfma_f32_16x16x32_bf16 v[4:7], v[154:157], v[210:213], v[4:7]
	v_mfma_f32_16x16x32_bf16 v[0:3], v[162:165], v[210:213], v[0:3]
	s_setprio 0
	s_barrier
	s_add_i32 s16, 0, 0x18000
	s_add_i32 s17, 0, 0x1c000
	v_add_u32_e32 v132, s16, v172
	v_add_u32_e32 v144, s17, v172
	ds_read_b128 v[128:131], v132
	ds_read_b128 v[132:135], v132 offset:1024
	ds_read_b128 v[136:139], v178
	ds_read_b128 v[140:143], v178 offset:1024
	ds_read_b128 v[150:153], v144
	ds_read_b128 v[154:157], v144 offset:1024
	ds_read_b128 v[158:161], v179
	ds_read_b128 v[162:165], v179 offset:1024
	s_add_u32 s60, s50, 0x40000
	v_mov_b32_e32 v144, v168
	s_mov_b32 m0, s89
	ds_read_b128 v[182:185], v177 offset:32768
	ds_read_b128 v[186:189], v177 offset:33792
	ds_read_b128 v[190:193], v177 offset:34816
	ds_read_b128 v[194:197], v177 offset:35840
	ds_read_b128 v[198:201], v177 offset:36864
	ds_read_b128 v[202:205], v177 offset:37888
	ds_read_b128 v[206:209], v177 offset:38912
	ds_read_b128 v[210:213], v177 offset:39936
	s_addc_u32 s61, s51, 0
	s_nop 0
	global_load_lds_dwordx4 v144, s[60:61]
	v_mov_b32_e32 v144, v170
	s_mov_b32 m0, s90
	s_nop 0
	global_load_lds_dwordx4 v144, s[60:61]
	s_waitcnt vmcnt(8)
	s_waitcnt lgkmcnt(0)
	s_barrier
	s_setprio 1
	s_waitcnt lgkmcnt(0)
	v_mfma_f32_16x16x32_bf16 v[124:127], v[128:131], v[182:185], v[124:127]
	v_mfma_f32_16x16x32_bf16 v[120:123], v[136:139], v[182:185], v[120:123]
	v_mfma_f32_16x16x32_bf16 v[108:111], v[128:131], v[190:193], v[108:111]
	v_mfma_f32_16x16x32_bf16 v[104:107], v[136:139], v[190:193], v[104:107]
	v_mfma_f32_16x16x32_bf16 v[92:95], v[128:131], v[198:201], v[92:95]
	v_mfma_f32_16x16x32_bf16 v[88:91], v[136:139], v[198:201], v[88:91]
	v_mfma_f32_16x16x32_bf16 v[76:79], v[128:131], v[206:209], v[76:79]
	v_mfma_f32_16x16x32_bf16 v[72:75], v[136:139], v[206:209], v[72:75]
	s_setprio 0
	s_setprio 1
	v_mfma_f32_16x16x32_bf16 v[124:127], v[132:135], v[186:189], v[124:127]
	v_mfma_f32_16x16x32_bf16 v[120:123], v[140:143], v[186:189], v[120:123]
	v_mfma_f32_16x16x32_bf16 v[108:111], v[132:135], v[194:197], v[108:111]
	v_mfma_f32_16x16x32_bf16 v[104:107], v[140:143], v[194:197], v[104:107]
	v_mfma_f32_16x16x32_bf16 v[92:95], v[132:135], v[202:205], v[92:95]
	v_mfma_f32_16x16x32_bf16 v[88:91], v[140:143], v[202:205], v[88:91]
	v_mfma_f32_16x16x32_bf16 v[76:79], v[132:135], v[210:213], v[76:79]
	v_mfma_f32_16x16x32_bf16 v[72:75], v[140:143], v[210:213], v[72:75]
	s_setprio 0
	s_setprio 1
	v_mfma_f32_16x16x32_bf16 v[116:119], v[150:153], v[182:185], v[116:119]
	v_mfma_f32_16x16x32_bf16 v[112:115], v[158:161], v[182:185], v[112:115]
	v_mfma_f32_16x16x32_bf16 v[100:103], v[150:153], v[190:193], v[100:103]
	v_mfma_f32_16x16x32_bf16 v[96:99], v[158:161], v[190:193], v[96:99]
	v_mfma_f32_16x16x32_bf16 v[84:87], v[150:153], v[198:201], v[84:87]
	v_mfma_f32_16x16x32_bf16 v[80:83], v[158:161], v[198:201], v[80:83]
	v_mfma_f32_16x16x32_bf16 v[68:71], v[150:153], v[206:209], v[68:71]
	v_mfma_f32_16x16x32_bf16 v[64:67], v[158:161], v[206:209], v[64:67]
	s_setprio 0
	s_setprio 1
	v_mfma_f32_16x16x32_bf16 v[116:119], v[154:157], v[186:189], v[116:119]
	v_mfma_f32_16x16x32_bf16 v[112:115], v[162:165], v[186:189], v[112:115]
	v_mfma_f32_16x16x32_bf16 v[100:103], v[154:157], v[194:197], v[100:103]
	v_mfma_f32_16x16x32_bf16 v[96:99], v[162:165], v[194:197], v[96:99]
	v_mfma_f32_16x16x32_bf16 v[84:87], v[154:157], v[202:205], v[84:87]
	v_mfma_f32_16x16x32_bf16 v[80:83], v[162:165], v[202:205], v[80:83]
	v_mfma_f32_16x16x32_bf16 v[68:71], v[154:157], v[210:213], v[68:71]
	v_mfma_f32_16x16x32_bf16 v[64:67], v[162:165], v[210:213], v[64:67]
	s_setprio 0
	s_barrier
; #define PG8_LDA(dst, b, h) do { if constexpr (FP8) { _Pragma("unroll") for (int m = 0; m < 4; ++m) dst##8[m] = PG8_LD8(PG8_SA(b, h), aoff, aoff1, m); } \
;         else { _Pragma("unroll") for (int m = 0; m < 4; ++m) _Pragma("unroll") for (int k = 0; k < 2; ++k) dst[m][k] = *(const LAS bf16x8*)(lds + PG8_SA(b, h) + (k ? aoff1 : aoff) + m * 2048); } } while (0)
; #define PG8_WAIT_V(n) asm volatile("s_waitcnt vmcnt(" #n ")" ::: "memory")
; #define PG8_WAIT_L(n) asm volatile("s_waitcnt lgkmcnt(" #n ")" ::: "memory")
; #define PG8_BAR __builtin_amdgcn_s_barrier()
; #define PG8_SCHED __builtin_amdgcn_sched_barrier(0)
; #define PG8_S4 do { PG8_STAGE(PG8_SB(1, 0), b3, voffB); PG8_STAGE(PG8_SB(1, 1), b3 + hstepB, voffB); PG8_STAGE(PG8_SA(1, 0), a3, voffA); } while (0)
; template <class Epi, class SchedT, bool ALIGN_EPI, bool SP2, bool FP8 = false>
; __device__ __forceinline__ void gemm_phase(LAS unsigned char* lds, const Gemm g, const SchedT& S, const Epi& E, const int wid) {
;     ...
;         for (int t = 0; t < nt; t += 2) {
;     ...
;             PG8_LDA(At, 1, 1); PG8_S4;
;             PG8_WAIT_V(8); PG8_WAIT_L(0); PG8_BAR; PG8_MMAP(1, 1, 1); PG8_BAR; PG8_SCHED;
	v_mov_b32_e32 v144, v169
	ds_read_b128 v[182:185], v177 offset:49152
	ds_read_b128 v[186:189], v177 offset:50176
	ds_read_b128 v[190:193], v177 offset:51200
	ds_read_b128 v[194:197], v177 offset:52224
	ds_read_b128 v[198:201], v177 offset:53248
	ds_read_b128 v[202:205], v177 offset:54272
	ds_read_b128 v[206:209], v177 offset:55296
	ds_read_b128 v[210:213], v177 offset:56320
	s_add_i32 s16, s16, s86
	v_lshl_add_u64 v[166:167], s[52:53], 0, v[144:145]
	v_lshl_add_u64 v[166:167], v[166:167], 0, s[6:7]
	s_mov_b32 m0, s16
	v_mov_b32_e32 v144, v171
	global_load_lds_dwordx4 v[166:167], off
	s_add_i32 m0, s16, 0x2000
	s_nop 0
	v_lshl_add_u64 v[166:167], s[52:53], 0, v[144:145]
	s_add_u32 s52, s52, 0x40080
	v_lshl_add_u64 v[166:167], v[166:167], 0, s[6:7]
	s_addc_u32 s53, s53, 0
	v_mov_b32_e32 v144, v169
	s_add_i32 s16, s17, s86
	global_load_lds_dwordx4 v[166:167], off
	s_mov_b32 m0, s16
	s_nop 0
	global_load_lds_dwordx4 v144, s[52:53]
	v_mov_b32_e32 v144, v171
	s_add_i32 m0, s16, 0x2000
	s_nop 0
	global_load_lds_dwordx4 v144, s[52:53]
	v_mov_b32_e32 v144, v168
	s_mov_b32 m0, s92
	v_lshl_add_u64 v[166:167], s[50:51], 0, v[144:145]
	v_lshl_add_u64 v[166:167], v[166:167], 0, s[6:7]
	v_mov_b32_e32 v144, v170
	global_load_lds_dwordx4 v[166:167], off
	s_mov_b32 m0, s93
	v_lshl_add_u64 v[166:167], s[50:51], 0, v[144:145]
	v_lshl_add_u64 v[166:167], v[166:167], 0, s[6:7]
	global_load_lds_dwordx4 v[166:167], off
	s_waitcnt vmcnt(8)
	s_waitcnt lgkmcnt(0)
	s_barrier
	s_setprio 1
	s_waitcnt lgkmcnt(0)
	v_mfma_f32_16x16x32_bf16 v[60:63], v[128:131], v[182:185], v[60:63]
	v_mfma_f32_16x16x32_bf16 v[56:59], v[136:139], v[182:185], v[56:59]
	v_mfma_f32_16x16x32_bf16 v[44:47], v[128:131], v[190:193], v[44:47]
	v_mfma_f32_16x16x32_bf16 v[40:43], v[136:139], v[190:193], v[40:43]
	v_mfma_f32_16x16x32_bf16 v[28:31], v[128:131], v[198:201], v[28:31]
	v_mfma_f32_16x16x32_bf16 v[24:27], v[136:139], v[198:201], v[24:27]
	v_mfma_f32_16x16x32_bf16 v[12:15], v[128:131], v[206:209], v[12:15]
	v_mfma_f32_16x16x32_bf16 v[8:11], v[136:139], v[206:209], v[8:11]
	s_setprio 0
	s_setprio 1
	v_mfma_f32_16x16x32_bf16 v[60:63], v[132:135], v[186:189], v[60:63]
	v_mfma_f32_16x16x32_bf16 v[56:59], v[140:143], v[186:189], v[56:59]
	v_mfma_f32_16x16x32_bf16 v[44:47], v[132:135], v[194:197], v[44:47]
	v_mfma_f32_16x16x32_bf16 v[40:43], v[140:143], v[194:197], v[40:43]
	v_mfma_f32_16x16x32_bf16 v[28:31], v[132:135], v[202:205], v[28:31]
	v_mfma_f32_16x16x32_bf16 v[24:27], v[140:143], v[202:205], v[24:27]
	v_mfma_f32_16x16x32_bf16 v[12:15], v[132:135], v[210:213], v[12:15]
	v_mfma_f32_16x16x32_bf16 v[8:11], v[140:143], v[210:213], v[8:11]
	s_setprio 0
	s_setprio 1
	v_mfma_f32_16x16x32_bf16 v[52:55], v[150:153], v[182:185], v[52:55]
	v_mfma_f32_16x16x32_bf16 v[48:51], v[158:161], v[182:185], v[48:51]
	v_mfma_f32_16x16x32_bf16 v[36:39], v[150:153], v[190:193], v[36:39]
	v_mfma_f32_16x16x32_bf16 v[32:35], v[158:161], v[190:193], v[32:35]
	v_mfma_f32_16x16x32_bf16 v[20:23], v[150:153], v[198:201], v[20:23]
	v_mfma_f32_16x16x32_bf16 v[16:19], v[158:161], v[198:201], v[16:19]
	v_mfma_f32_16x16x32_bf16 v[4:7], v[150:153], v[206:209], v[4:7]
	v_mfma_f32_16x16x32_bf16 v[0:3], v[158:161], v[206:209], v[0:3]
	s_setprio 0
	s_setprio 1
	v_mfma_f32_16x16x32_bf16 v[52:55], v[154:157], v[186:189], v[52:55]
	v_mfma_f32_16x16x32_bf16 v[48:51], v[162:165], v[186:189], v[48:51]
	v_mfma_f32_16x16x32_bf16 v[36:39], v[154:157], v[194:197], v[36:39]
	v_mfma_f32_16x16x32_bf16 v[32:35], v[162:165], v[194:197], v[32:35]
	v_mfma_f32_16x16x32_bf16 v[20:23], v[154:157], v[202:205], v[20:23]
	v_mfma_f32_16x16x32_bf16 v[16:19], v[162:165], v[202:205], v[16:19]
	v_mfma_f32_16x16x32_bf16 v[4:7], v[154:157], v[210:213], v[4:7]
	v_mfma_f32_16x16x32_bf16 v[0:3], v[162:165], v[210:213], v[0:3]
	s_setprio 0
	s_barrier
	s_add_u32 s48, s48, 0x100
	s_addc_u32 s49, s49, 0
	s_add_u32 s30, s30, 0x100
	s_addc_u32 s31, s31, 0
	s_cmp_ge_i32 s35, s20
	s_mov_b32 s34, s35
	s_cbranch_scc0 .LBB0_899
	s_branch .LBB0_894

; #define PG8_LDA(dst, b, h) do { if constexpr (FP8) { _Pragma("unroll") for (int m = 0; m < 4; ++m) dst##8[m] = PG8_LD8(PG8_SA(b, h), aoff, aoff1, m); } \
;         else { _Pragma("unroll") for (int m = 0; m < 4; ++m) _Pragma("unroll") for (int k = 0; k < 2; ++k) dst[m][k] = *(const LAS bf16x8*)(lds + PG8_SA(b, h) + (k ? aoff1 : aoff) + m * 2048); } } while (0)
; #define PG8_LDB(dst, b, h) do { if constexpr (FP8) { dst##8[0] = PG8_LD8(PG8_SB(b, h), boff, boff1, 0); dst##8[1] = PG8_LD8(PG8_SB(b, h), boff, boff1, 1); } \
;         else { _Pragma("unroll") for (int n = 0; n < 2; ++n) _Pragma("unroll") for (int k = 0; k < 2; ++k) dst[n][k] = *(const LAS bf16x8*)(lds + PG8_SB(b, h) + (k ? boff1 : boff) + n * 2048); } } while (0)
; #define PG8_WAIT_V(n) asm volatile("s_waitcnt vmcnt(" #n ")" ::: "memory")
; #define PG8_WAIT_L(n) asm volatile("s_waitcnt lgkmcnt(" #n ")" ::: "memory")
; #define PG8_BAR __builtin_amdgcn_s_barrier()
; #define PG8_SCHED __builtin_amdgcn_sched_barrier(0)
; #define PG8_S1 PG8_STAGE(PG8_SA(1, 1), a1 + hstepA, voffA)
; #define PG8_S2 do { PG8_STAGE(PG8_SB(0, 0), b2, voffB); PG8_STAGE(PG8_SB(0, 1), b2 + hstepB, voffB); PG8_STAGE(PG8_SA(0, 0), a2, voffA); } while (0)
; template <class Epi, class SchedT, bool ALIGN_EPI, bool SP2, bool FP8 = false>
; __device__ __forceinline__ void gemm_phase(LAS unsigned char* lds, const Gemm g, const SchedT& S, const Epi& E, const int wid) {
;     ...
;             const bool last = (t == nt - 2);
;             const char* a1 = cA + (size_t)(t + 1) * kstep;
;             const char* a2 = last ? nA : cA + (size_t)(t + 2) * kstep; const char* b2 = last ? nB : cB + (size_t)(t + 2) * kstep;
;             const char* a3 = a2 + kstep; const char* b3 = b2 + kstep;
;             if constexpr (SP2) {
;     ...
;             PG8_LDB(B0, 0, 0); PG8_LDB(B1, 0, 1); PG8_SCHED; PG8_LDA(At, 0, 0); PG8_S1;
;             PG8_WAIT_V(8); PG8_WAIT_L(0); PG8_BAR; PG8_MMAP(0, 0, 0); PG8_BAR; PG8_SCHED;
;             PG8_LDA(At, 0, 1); PG8_S2;
;             PG8_WAIT_V(8); PG8_WAIT_L(0); PG8_BAR; PG8_MMAP(1, 0, 1); PG8_BAR; PG8_SCHED;
.LBB0_970:
	ds_read_b128 v[134:137], v175
	ds_read_b128 v[138:141], v175 offset:1024
	ds_read_b128 v[142:145], v176
	ds_read_b128 v[146:149], v176 offset:1024
	ds_read_b128 v[150:153], v177
	ds_read_b128 v[154:157], v177 offset:1024
	ds_read_b128 v[158:161], v178
	ds_read_b128 v[162:165], v178 offset:1024
	s_add_i32 s48, s34, 2
	s_add_u32 s16, s24, 0xfff00080
	s_addc_u32 s17, s25, -1
	s_cmp_eq_u32 s45, s34
	s_cselect_b32 s34, s15, s16
	s_cselect_b32 s35, s13, s17
	s_cselect_b32 s39, s27, s47
	s_cselect_b32 s38, s31, s46
	v_mov_b32_e32 v128, v172
	ds_read_b128 v[166:169], v179
	ds_read_b128 v[184:187], v179 offset:1024
	ds_read_b128 v[188:191], v179 offset:2048
	ds_read_b128 v[192:195], v179 offset:3072
	ds_read_b128 v[196:199], v179 offset:4096
	ds_read_b128 v[200:203], v179 offset:5120
	ds_read_b128 v[204:207], v179 offset:6144
	ds_read_b128 v[208:211], v179 offset:7168
	s_add_i32 m0, s87, 0xc000
	s_nop 0
	global_load_lds_dwordx4 v128, s[24:25]
	v_mov_b32_e32 v128, v173
	s_add_i32 m0, s87, 0xe000
	s_nop 0
	global_load_lds_dwordx4 v128, s[24:25]
	s_waitcnt vmcnt(8)
	s_waitcnt lgkmcnt(0)
	s_barrier
	s_setprio 1
	s_waitcnt lgkmcnt(0)
	v_mfma_f32_16x16x32_bf16 v[124:127], v[134:137], v[166:169], v[124:127]
	v_mfma_f32_16x16x32_bf16 v[120:123], v[142:145], v[166:169], v[120:123]
	v_mfma_f32_16x16x32_bf16 v[108:111], v[134:137], v[188:191], v[108:111]
	v_mfma_f32_16x16x32_bf16 v[104:107], v[142:145], v[188:191], v[104:107]
	v_mfma_f32_16x16x32_bf16 v[92:95], v[134:137], v[196:199], v[92:95]
	v_mfma_f32_16x16x32_bf16 v[88:91], v[142:145], v[196:199], v[88:91]
	v_mfma_f32_16x16x32_bf16 v[76:79], v[134:137], v[204:207], v[76:79]
	v_mfma_f32_16x16x32_bf16 v[72:75], v[142:145], v[204:207], v[72:75]
	s_setprio 0
	s_setprio 1
	v_mfma_f32_16x16x32_bf16 v[124:127], v[138:141], v[184:187], v[124:127]
	v_mfma_f32_16x16x32_bf16 v[120:123], v[146:149], v[184:187], v[120:123]
	v_mfma_f32_16x16x32_bf16 v[108:111], v[138:141], v[192:195], v[108:111]
	v_mfma_f32_16x16x32_bf16 v[104:107], v[146:149], v[192:195], v[104:107]
	v_mfma_f32_16x16x32_bf16 v[92:95], v[138:141], v[200:203], v[92:95]
	v_mfma_f32_16x16x32_bf16 v[88:91], v[146:149], v[200:203], v[88:91]
	v_mfma_f32_16x16x32_bf16 v[76:79], v[138:141], v[208:211], v[76:79]
	v_mfma_f32_16x16x32_bf16 v[72:75], v[146:149], v[208:211], v[72:75]
	s_setprio 0
	s_setprio 1
	v_mfma_f32_16x16x32_bf16 v[116:119], v[150:153], v[166:169], v[116:119]
	v_mfma_f32_16x16x32_bf16 v[112:115], v[158:161], v[166:169], v[112:115]
	v_mfma_f32_16x16x32_bf16 v[100:103], v[150:153], v[188:191], v[100:103]
	v_mfma_f32_16x16x32_bf16 v[96:99], v[158:161], v[188:191], v[96:99]
	v_mfma_f32_16x16x32_bf16 v[84:87], v[150:153], v[196:199], v[84:87]
	v_mfma_f32_16x16x32_bf16 v[80:83], v[158:161], v[196:199], v[80:83]
	v_mfma_f32_16x16x32_bf16 v[68:71], v[150:153], v[204:207], v[68:71]
	v_mfma_f32_16x16x32_bf16 v[64:67], v[158:161], v[204:207], v[64:67]
	s_setprio 0
	s_setprio 1
	v_mfma_f32_16x16x32_bf16 v[116:119], v[154:157], v[184:187], v[116:119]
	v_mfma_f32_16x16x32_bf16 v[112:115], v[162:165], v[184:187], v[112:115]
	v_mfma_f32_16x16x32_bf16 v[100:103], v[154:157], v[192:195], v[100:103]
	v_mfma_f32_16x16x32_bf16 v[96:99], v[162:165], v[192:195], v[96:99]
	v_mfma_f32_16x16x32_bf16 v[84:87], v[154:157], v[200:203], v[84:87]
	v_mfma_f32_16x16x32_bf16 v[80:83], v[162:165], v[200:203], v[80:83]
	v_mfma_f32_16x16x32_bf16 v[68:71], v[154:157], v[208:211], v[68:71]
	v_mfma_f32_16x16x32_bf16 v[64:67], v[162:165], v[208:211], v[64:67]
	s_setprio 0
	s_barrier
	v_mov_b32_e32 v128, v172
	s_add_i32 s16, s94, s86
	ds_read_b128 v[166:169], v179 offset:16384
	ds_read_b128 v[184:187], v179 offset:17408
	ds_read_b128 v[188:191], v179 offset:18432
	ds_read_b128 v[192:195], v179 offset:19456
	ds_read_b128 v[196:199], v179 offset:20480
	ds_read_b128 v[200:203], v179 offset:21504
	ds_read_b128 v[204:207], v179 offset:22528
	ds_read_b128 v[208:211], v179 offset:23552
	s_mov_b32 m0, s16
	s_nop 0
	global_load_lds_dwordx4 v128, s[38:39]
	v_mov_b32_e32 v128, v173
	s_add_i32 m0, s16, 0x2000
	s_add_u32 s50, s38, 0x100000
	global_load_lds_dwordx4 v128, s[38:39]
	s_addc_u32 s51, s39, 0
	v_mov_b32_e32 v128, v172
	s_add_i32 s16, s95, s86
	s_mov_b32 m0, s16
	s_nop 0
	global_load_lds_dwordx4 v128, s[50:51]
	v_mov_b32_e32 v128, v173
	s_add_i32 m0, s16, 0x2000
	s_nop 0
	global_load_lds_dwordx4 v128, s[50:51]
	v_mov_b32_e32 v128, v172
	s_mov_b32 m0, s87
	s_nop 0
	global_load_lds_dwordx4 v128, s[34:35]
	v_mov_b32_e32 v128, v173
	s_mov_b32 m0, s88
	s_nop 0
	global_load_lds_dwordx4 v128, s[34:35]
	s_waitcnt vmcnt(8)
	s_waitcnt lgkmcnt(0)
	s_barrier
; #define PG8_LDA(dst, b, h) do { if constexpr (FP8) { _Pragma("unroll") for (int m = 0; m < 4; ++m) dst##8[m] = PG8_LD8(PG8_SA(b, h), aoff, aoff1, m); } \
;         else { _Pragma("unroll") for (int m = 0; m < 4; ++m) _Pragma("unroll") for (int k = 0; k < 2; ++k) dst[m][k] = *(const LAS bf16x8*)(lds + PG8_SA(b, h) + (k ? aoff1 : aoff) + m * 2048); } } while (0)
; #define PG8_LDB(dst, b, h) do { if constexpr (FP8) { dst##8[0] = PG8_LD8(PG8_SB(b, h), boff, boff1, 0); dst##8[1] = PG8_LD8(PG8_SB(b, h), boff, boff1, 1); } \
;         else { _Pragma("unroll") for (int n = 0; n < 2; ++n) _Pragma("unroll") for (int k = 0; k < 2; ++k) dst[n][k] = *(const LAS bf16x8*)(lds + PG8_SB(b, h) + (k ? boff1 : boff) + n * 2048); } } while (0)
; #define PG8_WAIT_V(n) asm volatile("s_waitcnt vmcnt(" #n ")" ::: "memory")
; #define PG8_WAIT_L(n) asm volatile("s_waitcnt lgkmcnt(" #n ")" ::: "memory")
; #define PG8_BAR __builtin_amdgcn_s_barrier()
; #define PG8_SCHED __builtin_amdgcn_sched_barrier(0)
; #define PG8_S3 PG8_STAGE(PG8_SA(0, 1), a2 + hstepA, voffA)
; template <class Epi, class SchedT, bool ALIGN_EPI, bool SP2, bool FP8 = false>
; __device__ __forceinline__ void gemm_phase(LAS unsigned char* lds, const Gemm g, const SchedT& S, const Epi& E, const int wid) {
;     ...
;             PG8_WAIT_V(8); PG8_WAIT_L(0); PG8_BAR; PG8_MMAP(1, 0, 1); PG8_BAR; PG8_SCHED;
;             PG8_LDB(B0, 1, 0); PG8_LDB(B1, 1, 1); PG8_SCHED; PG8_LDA(At, 1, 0); PG8_S3;
;             PG8_WAIT_V(8); PG8_WAIT_L(0); PG8_BAR; PG8_MMAP(0, 1, 0); PG8_BAR; PG8_SCHED;
	s_setprio 1
	s_waitcnt lgkmcnt(0)
	v_mfma_f32_16x16x32_bf16 v[60:63], v[134:137], v[166:169], v[60:63]
	v_mfma_f32_16x16x32_bf16 v[56:59], v[142:145], v[166:169], v[56:59]
	v_mfma_f32_16x16x32_bf16 v[44:47], v[134:137], v[188:191], v[44:47]
	v_mfma_f32_16x16x32_bf16 v[40:43], v[142:145], v[188:191], v[40:43]
	v_mfma_f32_16x16x32_bf16 v[28:31], v[134:137], v[196:199], v[28:31]
	v_mfma_f32_16x16x32_bf16 v[24:27], v[142:145], v[196:199], v[24:27]
	v_mfma_f32_16x16x32_bf16 v[12:15], v[134:137], v[204:207], v[12:15]
	v_mfma_f32_16x16x32_bf16 v[8:11], v[142:145], v[204:207], v[8:11]
	s_setprio 0
	s_setprio 1
	v_mfma_f32_16x16x32_bf16 v[60:63], v[138:141], v[184:187], v[60:63]
	v_mfma_f32_16x16x32_bf16 v[56:59], v[146:149], v[184:187], v[56:59]
	v_mfma_f32_16x16x32_bf16 v[44:47], v[138:141], v[192:195], v[44:47]
	v_mfma_f32_16x16x32_bf16 v[40:43], v[146:149], v[192:195], v[40:43]
	v_mfma_f32_16x16x32_bf16 v[28:31], v[138:141], v[200:203], v[28:31]
	v_mfma_f32_16x16x32_bf16 v[24:27], v[146:149], v[200:203], v[24:27]
	v_mfma_f32_16x16x32_bf16 v[12:15], v[138:141], v[208:211], v[12:15]
	v_mfma_f32_16x16x32_bf16 v[8:11], v[146:149], v[208:211], v[8:11]
	s_setprio 0
	s_setprio 1
	v_mfma_f32_16x16x32_bf16 v[52:55], v[150:153], v[166:169], v[52:55]
	v_mfma_f32_16x16x32_bf16 v[48:51], v[158:161], v[166:169], v[48:51]
	v_mfma_f32_16x16x32_bf16 v[36:39], v[150:153], v[188:191], v[36:39]
	v_mfma_f32_16x16x32_bf16 v[32:35], v[158:161], v[188:191], v[32:35]
	v_mfma_f32_16x16x32_bf16 v[20:23], v[150:153], v[196:199], v[20:23]
	v_mfma_f32_16x16x32_bf16 v[16:19], v[158:161], v[196:199], v[16:19]
	v_mfma_f32_16x16x32_bf16 v[4:7], v[150:153], v[204:207], v[4:7]
	v_mfma_f32_16x16x32_bf16 v[0:3], v[158:161], v[204:207], v[0:3]
	s_setprio 0
	s_setprio 1
	v_mfma_f32_16x16x32_bf16 v[52:55], v[154:157], v[184:187], v[52:55]
	v_mfma_f32_16x16x32_bf16 v[48:51], v[162:165], v[184:187], v[48:51]
	v_mfma_f32_16x16x32_bf16 v[36:39], v[154:157], v[192:195], v[36:39]
	v_mfma_f32_16x16x32_bf16 v[32:35], v[162:165], v[192:195], v[32:35]
	v_mfma_f32_16x16x32_bf16 v[20:23], v[154:157], v[200:203], v[20:23]
	v_mfma_f32_16x16x32_bf16 v[16:19], v[162:165], v[200:203], v[16:19]
	v_mfma_f32_16x16x32_bf16 v[4:7], v[154:157], v[208:211], v[4:7]
	v_mfma_f32_16x16x32_bf16 v[0:3], v[162:165], v[208:211], v[0:3]
	s_setprio 0
	s_barrier
	s_add_i32 s16, 0, 0x18000
	v_add_u32_e32 v128, s16, v174
	s_add_i32 s17, 0, 0x1c000
	ds_read_b128 v[134:137], v128
	ds_read_b128 v[138:141], v128 offset:1024
	ds_read_b128 v[142:145], v180
	ds_read_b128 v[146:149], v180 offset:1024
	v_add_u32_e32 v128, s17, v174
	ds_read_b128 v[150:153], v128
	ds_read_b128 v[154:157], v128 offset:1024
	ds_read_b128 v[158:161], v181
	ds_read_b128 v[162:165], v181 offset:1024
	s_add_u32 s50, s34, 0x100000
	v_mov_b32_e32 v128, v172
	s_mov_b32 m0, s89
	ds_read_b128 v[166:169], v179 offset:32768
	ds_read_b128 v[184:187], v179 offset:33792
	ds_read_b128 v[188:191], v179 offset:34816
	ds_read_b128 v[192:195], v179 offset:35840
	ds_read_b128 v[196:199], v179 offset:36864
	ds_read_b128 v[200:203], v179 offset:37888
	ds_read_b128 v[204:207], v179 offset:38912
	ds_read_b128 v[208:211], v179 offset:39936
	s_addc_u32 s51, s35, 0
	s_nop 0
	global_load_lds_dwordx4 v128, s[50:51]
	v_mov_b32_e32 v128, v173
	s_mov_b32 m0, s90
	s_nop 0
	global_load_lds_dwordx4 v128, s[50:51]
	s_waitcnt vmcnt(8)
	s_waitcnt lgkmcnt(0)
	s_barrier
	s_setprio 1
	s_waitcnt lgkmcnt(0)
	v_mfma_f32_16x16x32_bf16 v[124:127], v[134:137], v[166:169], v[124:127]
	v_mfma_f32_16x16x32_bf16 v[120:123], v[142:145], v[166:169], v[120:123]
	v_mfma_f32_16x16x32_bf16 v[108:111], v[134:137], v[188:191], v[108:111]
	v_mfma_f32_16x16x32_bf16 v[104:107], v[142:145], v[188:191], v[104:107]
	v_mfma_f32_16x16x32_bf16 v[92:95], v[134:137], v[196:199], v[92:95]
	v_mfma_f32_16x16x32_bf16 v[88:91], v[142:145], v[196:199], v[88:91]
	v_mfma_f32_16x16x32_bf16 v[76:79], v[134:137], v[204:207], v[76:79]
	v_mfma_f32_16x16x32_bf16 v[72:75], v[142:145], v[204:207], v[72:75]
	s_setprio 0
	s_setprio 1
	v_mfma_f32_16x16x32_bf16 v[124:127], v[138:141], v[184:187], v[124:127]
	v_mfma_f32_16x16x32_bf16 v[120:123], v[146:149], v[184:187], v[120:123]
	v_mfma_f32_16x16x32_bf16 v[108:111], v[138:141], v[192:195], v[108:111]
	v_mfma_f32_16x16x32_bf16 v[104:107], v[146:149], v[192:195], v[104:107]
	v_mfma_f32_16x16x32_bf16 v[92:95], v[138:141], v[200:203], v[92:95]
	v_mfma_f32_16x16x32_bf16 v[88:91], v[146:149], v[200:203], v[88:91]
	v_mfma_f32_16x16x32_bf16 v[76:79], v[138:141], v[208:211], v[76:79]
	v_mfma_f32_16x16x32_bf16 v[72:75], v[146:149], v[208:211], v[72:75]
	s_setprio 0
	s_setprio 1
	v_mfma_f32_16x16x32_bf16 v[116:119], v[150:153], v[166:169], v[116:119]
	v_mfma_f32_16x16x32_bf16 v[112:115], v[158:161], v[166:169], v[112:115]
	v_mfma_f32_16x16x32_bf16 v[100:103], v[150:153], v[188:191], v[100:103]
	v_mfma_f32_16x16x32_bf16 v[96:99], v[158:161], v[188:191], v[96:99]
	v_mfma_f32_16x16x32_bf16 v[84:87], v[150:153], v[196:199], v[84:87]
	v_mfma_f32_16x16x32_bf16 v[80:83], v[158:161], v[196:199], v[80:83]
	v_mfma_f32_16x16x32_bf16 v[68:71], v[150:153], v[204:207], v[68:71]
	v_mfma_f32_16x16x32_bf16 v[64:67], v[158:161], v[204:207], v[64:67]
	s_setprio 0
	s_setprio 1
	v_mfma_f32_16x16x32_bf16 v[116:119], v[154:157], v[184:187], v[116:119]
	v_mfma_f32_16x16x32_bf16 v[112:115], v[162:165], v[184:187], v[112:115]
	v_mfma_f32_16x16x32_bf16 v[100:103], v[154:157], v[192:195], v[100:103]
	v_mfma_f32_16x16x32_bf16 v[96:99], v[162:165], v[192:195], v[96:99]
	v_mfma_f32_16x16x32_bf16 v[84:87], v[154:157], v[200:203], v[84:87]
	v_mfma_f32_16x16x32_bf16 v[80:83], v[162:165], v[200:203], v[80:83]
	v_mfma_f32_16x16x32_bf16 v[68:71], v[154:157], v[208:211], v[68:71]
	v_mfma_f32_16x16x32_bf16 v[64:67], v[162:165], v[208:211], v[64:67]
	s_setprio 0
	s_barrier
; #define PG8_LDA(dst, b, h) do { if constexpr (FP8) { _Pragma("unroll") for (int m = 0; m < 4; ++m) dst##8[m] = PG8_LD8(PG8_SA(b, h), aoff, aoff1, m); } \
;         else { _Pragma("unroll") for (int m = 0; m < 4; ++m) _Pragma("unroll") for (int k = 0; k < 2; ++k) dst[m][k] = *(const LAS bf16x8*)(lds + PG8_SA(b, h) + (k ? aoff1 : aoff) + m * 2048); } } while (0)
; #define PG8_WAIT_V(n) asm volatile("s_waitcnt vmcnt(" #n ")" ::: "memory")
; #define PG8_WAIT_L(n) asm volatile("s_waitcnt lgkmcnt(" #n ")" ::: "memory")
; #define PG8_BAR __builtin_amdgcn_s_barrier()
; #define PG8_SCHED __builtin_amdgcn_sched_barrier(0)
; #define PG8_S4 do { PG8_STAGE(PG8_SB(1, 0), b3, voffB); PG8_STAGE(PG8_SB(1, 1), b3 + hstepB, voffB); PG8_STAGE(PG8_SA(1, 0), a3, voffA); } while (0)
; template <class Epi, class SchedT, bool ALIGN_EPI, bool SP2, bool FP8 = false>
; __device__ __forceinline__ void gemm_phase(LAS unsigned char* lds, const Gemm g, const SchedT& S, const Epi& E, const int wid) {
;     ...
;         for (int t = 0; t < nt; t += 2) {
;     ...
;             PG8_LDA(At, 1, 1); PG8_S4;
;             PG8_WAIT_V(8); PG8_WAIT_L(0); PG8_BAR; PG8_MMAP(1, 1, 1); PG8_BAR; PG8_SCHED;
	v_mov_b32_e32 v128, v172
	ds_read_b128 v[166:169], v179 offset:49152
	ds_read_b128 v[184:187], v179 offset:50176
	ds_read_b128 v[188:191], v179 offset:51200
	ds_read_b128 v[192:195], v179 offset:52224
	ds_read_b128 v[196:199], v179 offset:53248
	ds_read_b128 v[200:203], v179 offset:54272
	ds_read_b128 v[204:207], v179 offset:55296
	ds_read_b128 v[208:211], v179 offset:56320
	s_add_i32 s16, s16, s86
	v_lshl_add_u64 v[170:171], s[38:39], 0, v[128:129]
	v_lshl_add_u64 v[170:171], v[170:171], 0, s[8:9]
	s_mov_b32 m0, s16
	v_mov_b32_e32 v128, v173
	global_load_lds_dwordx4 v[170:171], off
	s_add_i32 m0, s16, 0x2000
	s_nop 0
	v_lshl_add_u64 v[170:171], s[38:39], 0, v[128:129]
	s_add_u32 s38, s38, 0x100080
	v_lshl_add_u64 v[170:171], v[170:171], 0, s[8:9]
	s_addc_u32 s39, s39, 0
	v_mov_b32_e32 v128, v172
	s_add_i32 s16, s17, s86
	global_load_lds_dwordx4 v[170:171], off
	s_mov_b32 m0, s16
	s_nop 0
	global_load_lds_dwordx4 v128, s[38:39]
	v_mov_b32_e32 v128, v173
	s_add_i32 m0, s16, 0x2000
	s_nop 0
	global_load_lds_dwordx4 v128, s[38:39]
	v_mov_b32_e32 v128, v172
	s_mov_b32 m0, s92
	v_lshl_add_u64 v[170:171], s[34:35], 0, v[128:129]
	v_lshl_add_u64 v[170:171], v[170:171], 0, s[8:9]
	v_mov_b32_e32 v128, v173
	global_load_lds_dwordx4 v[170:171], off
	s_mov_b32 m0, s93
	v_lshl_add_u64 v[170:171], s[34:35], 0, v[128:129]
	v_lshl_add_u64 v[170:171], v[170:171], 0, s[8:9]
	global_load_lds_dwordx4 v[170:171], off
	s_waitcnt vmcnt(8)
	s_waitcnt lgkmcnt(0)
	s_barrier
	s_setprio 1
	s_waitcnt lgkmcnt(0)
	v_mfma_f32_16x16x32_bf16 v[60:63], v[134:137], v[166:169], v[60:63]
	v_mfma_f32_16x16x32_bf16 v[56:59], v[142:145], v[166:169], v[56:59]
	v_mfma_f32_16x16x32_bf16 v[44:47], v[134:137], v[188:191], v[44:47]
	v_mfma_f32_16x16x32_bf16 v[40:43], v[142:145], v[188:191], v[40:43]
	v_mfma_f32_16x16x32_bf16 v[28:31], v[134:137], v[196:199], v[28:31]
	v_mfma_f32_16x16x32_bf16 v[24:27], v[142:145], v[196:199], v[24:27]
	v_mfma_f32_16x16x32_bf16 v[12:15], v[134:137], v[204:207], v[12:15]
	v_mfma_f32_16x16x32_bf16 v[8:11], v[142:145], v[204:207], v[8:11]
	s_setprio 0
	s_setprio 1
	v_mfma_f32_16x16x32_bf16 v[60:63], v[138:141], v[184:187], v[60:63]
	v_mfma_f32_16x16x32_bf16 v[56:59], v[146:149], v[184:187], v[56:59]
	v_mfma_f32_16x16x32_bf16 v[44:47], v[138:141], v[192:195], v[44:47]
	v_mfma_f32_16x16x32_bf16 v[40:43], v[146:149], v[192:195], v[40:43]
	v_mfma_f32_16x16x32_bf16 v[28:31], v[138:141], v[200:203], v[28:31]
	v_mfma_f32_16x16x32_bf16 v[24:27], v[146:149], v[200:203], v[24:27]
	v_mfma_f32_16x16x32_bf16 v[12:15], v[138:141], v[208:211], v[12:15]
	v_mfma_f32_16x16x32_bf16 v[8:11], v[146:149], v[208:211], v[8:11]
	s_setprio 0
	s_setprio 1
	v_mfma_f32_16x16x32_bf16 v[52:55], v[150:153], v[166:169], v[52:55]
	v_mfma_f32_16x16x32_bf16 v[48:51], v[158:161], v[166:169], v[48:51]
	v_mfma_f32_16x16x32_bf16 v[36:39], v[150:153], v[188:191], v[36:39]
	v_mfma_f32_16x16x32_bf16 v[32:35], v[158:161], v[188:191], v[32:35]
	v_mfma_f32_16x16x32_bf16 v[20:23], v[150:153], v[196:199], v[20:23]
	v_mfma_f32_16x16x32_bf16 v[16:19], v[158:161], v[196:199], v[16:19]
	v_mfma_f32_16x16x32_bf16 v[4:7], v[150:153], v[204:207], v[4:7]
	v_mfma_f32_16x16x32_bf16 v[0:3], v[158:161], v[204:207], v[0:3]
	s_setprio 0
	s_setprio 1
	v_mfma_f32_16x16x32_bf16 v[52:55], v[154:157], v[184:187], v[52:55]
	v_mfma_f32_16x16x32_bf16 v[48:51], v[162:165], v[184:187], v[48:51]
	v_mfma_f32_16x16x32_bf16 v[36:39], v[154:157], v[192:195], v[36:39]
	v_mfma_f32_16x16x32_bf16 v[32:35], v[162:165], v[192:195], v[32:35]
	v_mfma_f32_16x16x32_bf16 v[20:23], v[154:157], v[200:203], v[20:23]
	v_mfma_f32_16x16x32_bf16 v[16:19], v[162:165], v[200:203], v[16:19]
	v_mfma_f32_16x16x32_bf16 v[4:7], v[154:157], v[208:211], v[4:7]
	v_mfma_f32_16x16x32_bf16 v[0:3], v[162:165], v[208:211], v[0:3]
	s_setprio 0
	s_barrier
	s_add_u32 s24, s24, 0x100
	s_addc_u32 s25, s25, 0
	s_add_u32 s46, s46, 0x100
	s_addc_u32 s47, s47, 0
	s_cmp_ge_i32 s48, s30
	s_mov_b32 s34, s48
	s_cbranch_scc0 .LBB0_970
	s_and_b64 vcc, exec, s[96:97]
	s_cbranch_vccz .LBB0_973
